# GDN chain: chunk-top barrier removed (two workgroup barriers per chunk); exp(gc_last) read hoisted above the remaining mid-chunk barrier
# baseline (speedup 1.0000x reference)
; #define LAS __attribute__((address_space(3)))
; __device__ __forceinline__ unsigned pk2(float lo, float hi) { const f32v2_t f = {lo, hi}; const bf16v2_t b = __builtin_convertvector(f, bf16v2_t); return __builtin_bit_cast(unsigned, b); }
; #define WAVE_SYNC() do { asm volatile("s_waitcnt lgkmcnt(0)" ::: "memory"); __builtin_amdgcn_wave_barrier(); asm volatile("" ::: "memory"); } while (0)
; #define MFMA16(a, b, c) __builtin_amdgcn_mfma_f32_16x16x32_bf16((a), (b), (c), 0, 0, 0)
; template <int MODE>
; __device__ NOINL void chain_item(const LAS Params* lp, int l, int item, bool ctx_out, LAS unsigned char* lds) {
;     ...
;         for (int dk = 0; dk < NDK; ++dk) { u32x2 pk; pk.x = pk2(Sacc[dk][0], Sacc[dk][1]); pk.y = pk2(Sacc[dk][2], Sacc[dk][3]); *(LAS u32x2*)(ST + fr * 136 + 16 * dk + 4 * fq) = pk; }
;         WAVE_SYNC();
;         f32x4 qs[4], ksm[4];
; #pragma unroll
;         for (int ct = 0; ct < 4; ++ct) { qs[ct] = (f32x4){0.f, 0.f, 0.f, 0.f}; ksm[ct] = (f32x4){0.f, 0.f, 0.f, 0.f}; }
; #pragma unroll
;         for (int ks = 0; ks < NKS; ++ks) {
;             const bf16x8 Bf = *(const LAS bf16x8*)(ST + fr * 136 + ks * 32 + fq * 8);
; #pragma unroll
;             for (int ct = 0; ct < 4; ++ct) {
;                 const bf16x8 Aq = *(const LAS bf16x8*)(Qs + (16 * ct + fr) * 136 + kcol + ks * 32 + fq * 8);
;                 qs[ct] = MFMA16(Aq, Bf, qs[ct]);
;                 if (MODE == 0) { const bf16x8 Ak = *(const LAS bf16x8*)(Ks + (16 * ct + fr) * 136 + ks * 32 + fq * 8); ksm[ct] = MFMA16(Ak, Bf, ksm[ct]); }
;             }
;         }
.LBB0_1141:
	s_or_b64 exec, exec, s[62:63]
	ds_write_b16 v178, v68
	v_cvt_pk_bf16_f32 v68, v28, v29
	v_cvt_pk_bf16_f32 v69, v30, v31
	v_cvt_pk_bf16_f32 v70, v40, v41
	v_cvt_pk_bf16_f32 v71, v42, v43
	ds_write2_b64 v113, v[68:69], v[70:71] offset1:4
	v_cvt_pk_bf16_f32 v68, v32, v33
	v_cvt_pk_bf16_f32 v69, v34, v35
	v_cvt_pk_bf16_f32 v70, v36, v37
	v_cvt_pk_bf16_f32 v71, v38, v39
	ds_write2_b64 v113, v[68:69], v[70:71] offset0:8 offset1:12
	v_cvt_pk_bf16_f32 v68, v56, v57
	v_cvt_pk_bf16_f32 v69, v58, v59
	v_cvt_pk_bf16_f32 v70, v52, v53
	v_cvt_pk_bf16_f32 v71, v54, v55
	ds_write2_b64 v113, v[68:69], v[70:71] offset0:16 offset1:20
	v_cvt_pk_bf16_f32 v68, v44, v45
	v_cvt_pk_bf16_f32 v69, v46, v47
	v_cvt_pk_bf16_f32 v70, v48, v49
	v_cvt_pk_bf16_f32 v71, v50, v51
	ds_write2_b64 v113, v[68:69], v[70:71] offset0:24 offset1:28
	s_waitcnt lgkmcnt(0)
	v_add_u32_e32 v119, v113, v154
	ds_read_b128 v[84:87], v119
	ds_read_b128 v[100:103], v179
	ds_read_b128 v[104:107], v179 offset:17408
	ds_read_b128 v[194:197], v179 offset:4352
	ds_read_b128 v[236:239], v179 offset:21760
	ds_read_b128 v[240:243], v179 offset:8704
	ds_read_b128 v[244:247], v179 offset:26112
	ds_read_b128 v[248:251], v179 offset:13056
	v_add_u32_e32 v121, 0x25500, v110
	s_waitcnt lgkmcnt(6)
	v_mfma_f32_16x16x32_bf16 v[96:99], v[100:103], v[84:87], 0
	ds_read_b128 v[100:103], v179 offset:30464
	ds_read_b128 v[88:91], v119 offset:64
	s_add_i32 s5, s4, 4
	s_waitcnt lgkmcnt(7)
	v_mfma_f32_16x16x32_bf16 v[198:201], v[104:107], v[84:87], 0
	ds_read_b128 v[104:107], v179 offset:64
	s_and_b64 s[20:21], vcc, exec
	s_waitcnt lgkmcnt(7)
	v_mfma_f32_16x16x32_bf16 v[92:95], v[194:197], v[84:87], 0
	ds_read_b128 v[194:197], v179 offset:17472
	s_cselect_b32 s5, s1, s5
	s_waitcnt lgkmcnt(7)
	v_mfma_f32_16x16x32_bf16 v[232:235], v[236:239], v[84:87], 0
	ds_read_b128 v[236:239], v179 offset:4416
	s_add_i32 s22, s4, 40
	s_waitcnt lgkmcnt(7)
	v_mfma_f32_16x16x32_bf16 v[80:83], v[240:243], v[84:87], 0
	ds_read_b128 v[240:243], v179 offset:21824
	s_and_b64 s[20:21], vcc, exec
	s_waitcnt lgkmcnt(7)
	v_mfma_f32_16x16x32_bf16 v[72:75], v[244:247], v[84:87], 0
	ds_read_b128 v[244:247], v179 offset:8768
	s_cselect_b32 s20, s1, s22
	s_waitcnt lgkmcnt(7)
	v_mfma_f32_16x16x32_bf16 v[76:79], v[248:251], v[84:87], 0
	ds_read_b128 v[248:251], v179 offset:26176
	s_cmp_lt_u32 s1, 4
	s_waitcnt lgkmcnt(7)
	v_mfma_f32_16x16x32_bf16 v[68:71], v[100:103], v[84:87], 0
	ds_read_b128 v[100:103], v179 offset:13120
	s_cselect_b32 s1, s5, s20
	s_waitcnt lgkmcnt(6)
	v_mfma_f32_16x16x32_bf16 v[96:99], v[104:107], v[88:91], v[96:99]
	ds_read_b128 v[104:107], v179 offset:30528
	ds_read_b128 v[84:87], v119 offset:128
	s_lshl_b32 s5, s1, 6
	s_waitcnt lgkmcnt(7)
	v_mfma_f32_16x16x32_bf16 v[198:201], v[194:197], v[88:91], v[198:201]
	ds_read_b128 v[194:197], v179 offset:128
	s_add_i32 s20, s18, s5
	s_waitcnt lgkmcnt(7)
	v_mfma_f32_16x16x32_bf16 v[92:95], v[236:239], v[88:91], v[92:95]
	ds_read_b128 v[236:239], v179 offset:17536
	s_or_b32 s5, s5, s38
	s_waitcnt lgkmcnt(7)
	v_mfma_f32_16x16x32_bf16 v[232:235], v[240:243], v[88:91], v[232:235]
	ds_read_b128 v[240:243], v179 offset:4480
	s_cmp_lt_u32 s1, 4
	s_waitcnt lgkmcnt(7)
	v_mfma_f32_16x16x32_bf16 v[80:83], v[244:247], v[88:91], v[80:83]
	ds_read_b128 v[244:247], v179 offset:21888
	s_cselect_b32 s1, s5, s20
	s_waitcnt lgkmcnt(7)
	v_mfma_f32_16x16x32_bf16 v[72:75], v[248:251], v[88:91], v[72:75]
	ds_read_b128 v[248:251], v179 offset:8832
	s_mul_hi_i32 s21, s1, s19
	s_waitcnt lgkmcnt(7)
	v_mfma_f32_16x16x32_bf16 v[76:79], v[100:103], v[88:91], v[76:79]
	ds_read_b128 v[100:103], v179 offset:26240
	s_mul_i32 s20, s1, s19
	s_waitcnt lgkmcnt(7)
	v_mfma_f32_16x16x32_bf16 v[68:71], v[104:107], v[88:91], v[68:71]
	ds_read_b128 v[104:107], v179 offset:13184
	v_mov_b32_e32 v123, v1
	s_waitcnt lgkmcnt(6)
	v_mfma_f32_16x16x32_bf16 v[96:99], v[194:197], v[84:87], v[96:99]
	ds_read_b128 v[194:197], v179 offset:30592
	ds_read_b128 v[88:91], v119 offset:192
	v_add_u32_e32 v119, s34, v155
	v_mov_b32_e32 v125, v1
	s_waitcnt lgkmcnt(7)
	v_mfma_f32_16x16x32_bf16 v[198:201], v[236:239], v[84:87], v[198:201]
	ds_read_b128 v[236:239], v179 offset:192
	v_mov_b32_e32 v127, v1
	s_waitcnt lgkmcnt(7)
	v_mfma_f32_16x16x32_bf16 v[92:95], v[240:243], v[84:87], v[92:95]
	ds_read_b128 v[240:243], v179 offset:17600
	v_mov_b32_e32 v129, v1
	s_waitcnt lgkmcnt(7)
	v_mfma_f32_16x16x32_bf16 v[232:235], v[244:247], v[84:87], v[232:235]
	ds_read_b128 v[244:247], v179 offset:4544
	v_mov_b32_e32 v131, v1
	s_waitcnt lgkmcnt(7)
	v_mfma_f32_16x16x32_bf16 v[80:83], v[248:251], v[84:87], v[80:83]
	ds_read_b128 v[248:251], v179 offset:21952
	v_mov_b32_e32 v133, v1
	s_waitcnt lgkmcnt(7)
	v_mfma_f32_16x16x32_bf16 v[72:75], v[100:103], v[84:87], v[72:75]
	ds_read_b128 v[100:103], v179 offset:8896
	v_mov_b32_e32 v135, v1
	s_waitcnt lgkmcnt(7)
	v_mfma_f32_16x16x32_bf16 v[76:79], v[104:107], v[84:87], v[76:79]
	ds_read_b128 v[104:107], v179 offset:26304
	v_mov_b32_e32 v137, v1
	s_waitcnt lgkmcnt(7)
	v_mfma_f32_16x16x32_bf16 v[68:71], v[194:197], v[84:87], v[68:71]
	ds_read_b128 v[194:197], v179 offset:13248
	v_mov_b32_e32 v139, v1
	s_waitcnt lgkmcnt(6)
	v_mfma_f32_16x16x32_bf16 v[96:99], v[236:239], v[88:91], v[96:99]
	ds_read_b128 v[236:239], v179 offset:30656
	v_mov_b32_e32 v141, v1
	s_waitcnt lgkmcnt(6)
	v_mfma_f32_16x16x32_bf16 v[198:201], v[240:243], v[88:91], v[198:201]
	v_mov_b32_e32 v143, v1
	s_waitcnt lgkmcnt(5)
	v_mfma_f32_16x16x32_bf16 v[92:95], v[244:247], v[88:91], v[92:95]
	v_mov_b32_e32 v145, v1
	s_waitcnt lgkmcnt(4)
	v_mfma_f32_16x16x32_bf16 v[232:235], v[248:251], v[88:91], v[232:235]
	v_mov_b32_e32 v147, v1
	s_waitcnt lgkmcnt(3)
; #define LAS __attribute__((address_space(3)))
; __device__ __forceinline__ float bflo(unsigned u) { return __uint_as_float(u << 16); }
; template <int MODE>
; __device__ NOINL void chain_item(const LAS Params* lp, int l, int item, bool ctx_out, LAS unsigned char* lds) {
;     ...
;                 qs[ct] = MFMA16(Aq, Bf, qs[ct]);
;                 if (MODE == 0) { const bf16x8 Ak = *(const LAS bf16x8*)(Ks + (16 * ct + fr) * 136 + ks * 32 + fq * 8); ksm[ct] = MFMA16(Ak, Bf, ksm[ct]); }
;             }
;         }
;         float eg[4][4];
; #pragma unroll
;         for (int ct = 0; ct < 4; ++ct)
; #pragma unroll
;             for (int j = 0; j < 4; ++j) { const int c = 16 * ct + 4 * fq + j; eg[ct][j] = MODE == 0 ? gcs[128 + c] : __expf((float)(c + 1) * lg); }
;         bf16x8 Bv[2];
;         if (MODE == 0) {
; #pragma unroll
;             for (int ct = 0; ct < 4; ++ct) {
;                 const u32x2 vv = *(const LAS u32x2*)(VT + (dvrow + fr) * 72 + (((2 * ct + (fq >> 1)) ^ vkey) << 3) + 4 * (fq & 1));
;                 const float v4[4] = {bflo(vv.x), bfhi(vv.x), bflo(vv.y), bfhi(vv.y)};
;                 float r[4];
; #pragma unroll
;                 for (int j = 0; j < 4; ++j) r[j] = bts[16 * ct + 4 * fq + j] * (v4[j] - eg[ct][j] * ksm[ct][j]);
;                 u32x2 pk; pk.x = pk2(r[0], r[1]); pk.y = pk2(r[2], r[3]);
;                 *(LAS u32x2*)(RP + fr * 72 + 16 * ct + 4 * fq) = pk;
;             }
;             WAVE_SYNC();
;             bf16x8 Br[2];
;             Br[0] = *(const LAS bf16x8*)(RP + fr * 72 + fq * 8); Br[1] = *(const LAS bf16x8*)(RP + fr * 72 + 32 + fq * 8);
;             f32x4 vn[4];
; #pragma unroll
;             for (int ct = 0; ct < 4; ++ct) {
;                 vn[ct] = (f32x4){0.f, 0.f, 0.f, 0.f};
; #pragma unroll
;                 for (int ks = 0; ks < 2; ++ks) { const bf16x8 A = *(const LAS bf16x8*)(TT + (16 * ct + fr) * 72 + ks * 32 + fq * 8); vn[ct] = MFMA16(A, Br[ks], vn[ct]); }
;             }
;             WAVE_SYNC();
; #pragma unroll
;             for (int ct = 0; ct < 4; ++ct) { u32x2 pk; pk.x = pk2(vn[ct][0], vn[ct][1]); pk.y = pk2(vn[ct][2], vn[ct][3]); *(LAS u32x2*)(RP + fr * 72 + 16 * ct + 4 * fq) = pk; }
;             WAVE_SYNC();
;             Bv[0] = *(const LAS bf16x8*)(RP + fr * 72 + fq * 8); Bv[1] = *(const LAS bf16x8*)(RP + fr * 72 + 32 + fq * 8);
	v_mfma_f32_16x16x32_bf16 v[80:83], v[100:103], v[88:91], v[80:83]
	s_add_i32 s4, s4, -1
	s_waitcnt lgkmcnt(2)
	v_mfma_f32_16x16x32_bf16 v[72:75], v[104:107], v[88:91], v[72:75]
	s_cmp_lg_u32 s0, 36
	s_waitcnt lgkmcnt(1)
	v_mfma_f32_16x16x32_bf16 v[76:79], v[194:197], v[88:91], v[76:79]
	s_mov_b32 s1, s0
	s_waitcnt lgkmcnt(0)
	v_mfma_f32_16x16x32_bf16 v[68:71], v[236:239], v[88:91], v[68:71]
	ds_read_b64 v[88:89], v186 offset:53248
	ds_read_b128 v[104:107], v119 offset:512
	ds_read_b128 v[84:87], v121
	s_waitcnt lgkmcnt(2)
	v_lshlrev_b32_e32 v90, 16, v88
	v_and_b32_e32 v91, 0xffff0000, v88
	v_lshlrev_b32_e32 v88, 16, v89
	v_and_b32_e32 v89, 0xffff0000, v89
	s_waitcnt lgkmcnt(1)
	v_pk_fma_f32 v[90:91], v[198:199], v[104:105], v[90:91] neg_lo:[1,0,0] neg_hi:[1,0,0]
	v_pk_fma_f32 v[88:89], v[200:201], v[106:107], v[88:89] neg_lo:[1,0,0] neg_hi:[1,0,0]
	s_waitcnt lgkmcnt(0)
	v_pk_mul_f32 v[84:85], v[84:85], v[90:91]
	v_pk_mul_f32 v[86:87], v[86:87], v[88:89]
	v_cvt_pk_bf16_f32 v148, v84, v85
	v_cvt_pk_bf16_f32 v149, v86, v87
	ds_read_b128 v[100:103], v119 offset:576
	ds_read_b128 v[88:91], v119 offset:640
	ds_read_b128 v[84:87], v119 offset:704
	ds_write_b64 v158, v[148:149] offset:4352
	ds_read_b64 v[148:149], v187 offset:53248
	ds_read_b128 v[194:197], v121 offset:64
	v_add_u32_e32 v119, v158, v154
	s_waitcnt lgkmcnt(1)
	v_lshlrev_b32_e32 v198, 16, v148
	v_and_b32_e32 v199, 0xffff0000, v148
	v_lshlrev_b32_e32 v148, 16, v149
	v_and_b32_e32 v149, 0xffff0000, v149
	v_pk_fma_f32 v[198:199], v[232:233], v[100:101], v[198:199] neg_lo:[1,0,0] neg_hi:[1,0,0]
	v_pk_fma_f32 v[148:149], v[234:235], v[102:103], v[148:149] neg_lo:[1,0,0] neg_hi:[1,0,0]
	s_waitcnt lgkmcnt(0)
	v_pk_mul_f32 v[194:195], v[194:195], v[198:199]
	v_pk_mul_f32 v[148:149], v[196:197], v[148:149]
	v_cvt_pk_bf16_f32 v194, v194, v195
	v_cvt_pk_bf16_f32 v195, v148, v149
	ds_write_b64 v158, v[194:195] offset:4384
	ds_read_b64 v[148:149], v188 offset:53248
	ds_read_b128 v[194:197], v121 offset:128
	s_waitcnt lgkmcnt(1)
	v_lshlrev_b32_e32 v198, 16, v148
	v_and_b32_e32 v199, 0xffff0000, v148
	v_lshlrev_b32_e32 v148, 16, v149
	v_and_b32_e32 v149, 0xffff0000, v149
	v_pk_fma_f32 v[72:73], v[72:73], v[88:89], v[198:199] neg_lo:[1,0,0] neg_hi:[1,0,0]
	v_pk_fma_f32 v[74:75], v[74:75], v[90:91], v[148:149] neg_lo:[1,0,0] neg_hi:[1,0,0]
	s_waitcnt lgkmcnt(0)
	v_pk_mul_f32 v[72:73], v[194:195], v[72:73]
	v_pk_mul_f32 v[74:75], v[196:197], v[74:75]
	v_cvt_pk_bf16_f32 v72, v72, v73
	v_cvt_pk_bf16_f32 v73, v74, v75
	ds_write_b64 v158, v[72:73] offset:4416
	ds_read_b64 v[72:73], v189 offset:53248
	s_waitcnt lgkmcnt(0)
	v_lshlrev_b32_e32 v148, 16, v72
	v_and_b32_e32 v149, 0xffff0000, v72
	v_lshlrev_b32_e32 v194, 16, v73
	v_and_b32_e32 v195, 0xffff0000, v73
	ds_read_b128 v[72:75], v121 offset:192
	v_pk_fma_f32 v[68:69], v[68:69], v[84:85], v[148:149] neg_lo:[1,0,0] neg_hi:[1,0,0]
	v_pk_fma_f32 v[70:71], v[70:71], v[86:87], v[194:195] neg_lo:[1,0,0] neg_hi:[1,0,0]
	v_add_u32_e32 v121, v159, v157
	v_lshl_add_u64 v[148:149], s[20:21], 1, v[116:117]
	s_waitcnt lgkmcnt(0)
	v_pk_mul_f32 v[68:69], v[72:73], v[68:69]
	v_pk_mul_f32 v[70:71], v[74:75], v[70:71]
	v_cvt_pk_bf16_f32 v68, v68, v69
	v_cvt_pk_bf16_f32 v69, v70, v71
	ds_write_b64 v158, v[68:69] offset:4448
	s_waitcnt lgkmcnt(0)
	ds_read_b128 v[68:71], v119 offset:4352
	ds_read_b128 v[72:75], v119 offset:4416
	ds_read_b128 v[194:197], v121
	ds_read_b128 v[198:201], v121 offset:64
	s_waitcnt lgkmcnt(1)
	v_mfma_f32_16x16x32_bf16 v[194:197], v[194:197], v[68:71], 0
	v_add_u32_e32 v121, v159, v180
	ds_read_b128 v[232:235], v121 offset:64
	ds_read_b128 v[236:239], v121 offset:2368
	s_waitcnt lgkmcnt(2)
	v_mfma_f32_16x16x32_bf16 v[194:197], v[198:201], v[72:75], v[194:197]
	ds_read_b128 v[198:201], v121
	s_waitcnt lgkmcnt(0)
	v_mfma_f32_16x16x32_bf16 v[198:201], v[198:201], v[68:71], 0
	v_mfma_f32_16x16x32_bf16 v[198:201], v[232:235], v[72:75], v[198:201]
	ds_read_b128 v[232:235], v121 offset:2304
	s_waitcnt lgkmcnt(0)
	v_mfma_f32_16x16x32_bf16 v[232:235], v[232:235], v[68:71], 0
	v_mfma_f32_16x16x32_bf16 v[232:235], v[236:239], v[72:75], v[232:235]
	ds_read_b128 v[236:239], v121 offset:4608
	s_waitcnt lgkmcnt(0)
	v_mfma_f32_16x16x32_bf16 v[68:71], v[236:239], v[68:71], 0
	ds_read_b128 v[236:239], v121 offset:4672
	v_add_u32_e32 v121, 0x1000, v158
	s_waitcnt lgkmcnt(0)
	s_waitcnt lgkmcnt(0)
	v_mfma_f32_16x16x32_bf16 v[68:71], v[236:239], v[72:75], v[68:71]
	v_cvt_pk_bf16_f32 v72, v194, v195
	v_cvt_pk_bf16_f32 v73, v196, v197
	v_cvt_pk_bf16_f32 v74, v198, v199
	v_cvt_pk_bf16_f32 v75, v200, v201
	ds_write2_b64 v121, v[72:73], v[74:75] offset0:32 offset1:36
	v_cvt_pk_bf16_f32 v72, v232, v233
	v_cvt_pk_bf16_f32 v73, v234, v235
	s_nop 0
	v_cvt_pk_bf16_f32 v68, v68, v69
	v_cvt_pk_bf16_f32 v69, v70, v71
	ds_write2_b64 v121, v[72:73], v[68:69] offset0:40 offset1:44
	v_mov_b32_e32 v193, s17
	ds_read_b32 v193, v193
	s_waitcnt lgkmcnt(0)
	s_barrier
; #define LAS __attribute__((address_space(3)))
; __device__ __forceinline__ bf16_t f2bf(float f) { return (bf16_t)(pk2(f, f) & 0xFFFFu); }
; #define MFMA16(a, b, c) __builtin_amdgcn_mfma_f32_16x16x32_bf16((a), (b), (c), 0, 0, 0)
; template <int MODE>
; __device__ NOINL void chain_item(const LAS Params* lp, int l, int item, bool ctx_out, LAS unsigned char* lds) {
;     ...
;             Bv[0] = *(const LAS bf16x8*)(RP + fr * 72 + fq * 8); Bv[1] = *(const LAS bf16x8*)(RP + fr * 72 + 32 + fq * 8);
;         } else {
;             Bv[0] = *(const LAS bf16x8*)(VT + (dvrow + fr) * 72 + ((fq ^ vkey) << 3)); Bv[1] = *(const LAS bf16x8*)(VT + (dvrow + fr) * 72 + (((4 + fq) ^ vkey) << 3));
;         }
;         {
;             typedef __attribute__((address_space(1))) bf16_t gbf16;
;             bf16_t* ob; int ldo;
;             if (MODE == 0) { if (dir == 0) { ob = p.hbuf + 256 + h * 128 + 16 * w; ldo = 1024; } else { ob = p.hyproj + h * 128 + 16 * w; ldo = 768; } }
;             else { if (dir == 0) { ob = p.hbuf + 768 + (h + hh) * 64 + 16 * (w & 3); ldo = 1024; } else { ob = p.hyproj + 512 + (h + hh) * 64 + 16 * (w & 3); ldo = 768; } }
; #pragma unroll
;             for (int ct = 0; ct < 4; ++ct) {
;                 f32x4 acc = {0.f, 0.f, 0.f, 0.f};
; #pragma unroll
;                 for (int ks = 0; ks < 2; ++ks) { const bf16x8 A = *(const LAS bf16x8*)(AT + hh * 4608 + (16 * ct + fr) * 72 + ks * 32 + fq * 8); acc = MFMA16(A, Bv[ks], acc); }
;                 gbf16* og = (gbf16*)ob + (size_t)row0 * ldo + fr;
; #pragma unroll
;                 for (int j = 0; j < 4; ++j) { const int c = 16 * ct + 4 * fq + j, tok = dir ? 63 - c : c; og[tok * ldo] = f2bf(eg[ct][j] * qs[ct][j] + acc[j]); }
;             }
;         }
;         {
;             const float gl = MODE == 0 ? gcs[128 + 63] : __expf(64.f * lg);
; #pragma unroll
;             for (int dk = 0; dk < NDK; ++dk) {
;                 Sacc[dk] = Sacc[dk] * gl;
; #pragma unroll
;                 for (int ks = 0; ks < 2; ++ks) { const bf16x8 A = *(const LAS bf16x8*)(KT + (kcol + 16 * dk + fr) * 72 + (((ks * 4 + fq) ^ (((kcol >> 4) + dk) & 7)) << 3)); Sacc[dk] = MFMA16(A, Bv[ks], Sacc[dk]); }
	ds_read_b128 v[72:75], v119 offset:4352
	ds_read_b128 v[68:71], v119 offset:4416
	v_add_u32_e32 v218, v160, v157
	v_add_u32_e32 v219, v160, v180
	v_mov_b32_e32 v119, v1
	v_mov_b32_e32 v121, v1
	ds_read_b128 v[194:197], v218
	ds_read_b128 v[232:235], v219
	ds_read_b128 v[244:247], v219 offset:2304
	ds_read_b128 v[236:239], v219 offset:4608
	ds_read_b128 v[198:201], v218 offset:64
	ds_read_b128 v[240:243], v219 offset:64
	ds_read_b128 v[248:251], v219 offset:2368
	s_waitcnt lgkmcnt(6)
	v_mfma_f32_16x16x32_bf16 v[194:197], v[194:197], v[72:75], 0
	s_waitcnt lgkmcnt(5)
	v_mfma_f32_16x16x32_bf16 v[232:235], v[232:235], v[72:75], 0
	s_waitcnt lgkmcnt(4)
	v_mfma_f32_16x16x32_bf16 v[244:247], v[244:247], v[72:75], 0
	s_waitcnt lgkmcnt(3)
	v_mfma_f32_16x16x32_bf16 v[236:239], v[236:239], v[72:75], 0
	s_waitcnt lgkmcnt(2)
	v_mfma_f32_16x16x32_bf16 v[194:197], v[198:201], v[68:71], v[194:197]
	ds_read_b128 v[198:201], v219 offset:4672
	s_waitcnt lgkmcnt(2)
	v_mfma_f32_16x16x32_bf16 v[232:235], v[240:243], v[68:71], v[232:235]
	s_waitcnt lgkmcnt(1)
	v_mfma_f32_16x16x32_bf16 v[244:247], v[248:251], v[68:71], v[244:247]
	s_waitcnt lgkmcnt(0)
	v_mfma_f32_16x16x32_bf16 v[236:239], v[198:201], v[68:71], v[236:239]
	v_lshl_add_u64 v[240:241], v[148:149], 0, v[0:1]
	v_lshl_add_u64 v[242:243], v[148:149], 0, v[118:119]
	v_lshl_add_u64 v[248:249], v[148:149], 0, v[120:121]
	v_lshl_add_u64 v[250:251], v[148:149], 0, v[122:123]
	s_nop 3
	v_fma_f32 v194, v96, v104, v194
	v_fma_f32 v195, v97, v105, v195
	v_fma_f32 v196, v98, v106, v196
	v_fma_f32 v197, v99, v107, v197
	v_cvt_pk_bf16_f32 v194, v194, v194
	v_cvt_pk_bf16_f32 v195, v195, v195
	v_cvt_pk_bf16_f32 v196, v196, v196
	v_cvt_pk_bf16_f32 v197, v197, v197
	global_store_short v[240:241], v194, off
	global_store_short v[242:243], v195, off
	global_store_short v[248:249], v196, off
	global_store_short v[250:251], v197, off
	v_lshl_add_u64 v[240:241], v[148:149], 0, v[124:125]
	v_lshl_add_u64 v[242:243], v[148:149], 0, v[126:127]
	v_lshl_add_u64 v[248:249], v[148:149], 0, v[128:129]
	v_lshl_add_u64 v[250:251], v[148:149], 0, v[130:131]
	v_fma_f32 v232, v92, v100, v232
	v_fma_f32 v233, v93, v101, v233
	v_fma_f32 v234, v94, v102, v234
	v_fma_f32 v235, v95, v103, v235
	v_cvt_pk_bf16_f32 v232, v232, v232
	v_cvt_pk_bf16_f32 v233, v233, v233
	v_cvt_pk_bf16_f32 v234, v234, v234
	v_cvt_pk_bf16_f32 v235, v235, v235
	global_store_short v[240:241], v232, off
	global_store_short v[242:243], v233, off
	global_store_short v[248:249], v234, off
	global_store_short v[250:251], v235, off
	v_lshl_add_u64 v[240:241], v[148:149], 0, v[132:133]
	v_lshl_add_u64 v[242:243], v[148:149], 0, v[134:135]
	v_lshl_add_u64 v[248:249], v[148:149], 0, v[136:137]
	v_lshl_add_u64 v[250:251], v[148:149], 0, v[138:139]
	v_fma_f32 v244, v80, v88, v244
	v_fma_f32 v245, v81, v89, v245
	v_fma_f32 v246, v82, v90, v246
	v_fma_f32 v247, v83, v91, v247
	v_cvt_pk_bf16_f32 v244, v244, v244
	v_cvt_pk_bf16_f32 v245, v245, v245
	v_cvt_pk_bf16_f32 v246, v246, v246
	v_cvt_pk_bf16_f32 v247, v247, v247
	global_store_short v[240:241], v244, off
	global_store_short v[242:243], v245, off
	global_store_short v[248:249], v246, off
	global_store_short v[250:251], v247, off
	v_lshl_add_u64 v[240:241], v[148:149], 0, v[140:141]
	v_lshl_add_u64 v[242:243], v[148:149], 0, v[142:143]
	v_lshl_add_u64 v[248:249], v[148:149], 0, v[144:145]
	v_lshl_add_u64 v[250:251], v[148:149], 0, v[146:147]
	v_fma_f32 v236, v76, v84, v236
	v_fma_f32 v237, v77, v85, v237
	v_fma_f32 v238, v78, v86, v238
	v_fma_f32 v239, v79, v87, v239
	v_cvt_pk_bf16_f32 v236, v236, v236
	v_cvt_pk_bf16_f32 v237, v237, v237
	v_cvt_pk_bf16_f32 v238, v238, v238
	v_cvt_pk_bf16_f32 v239, v239, v239
	global_store_short v[240:241], v236, off
	global_store_short v[242:243], v237, off
	global_store_short v[248:249], v238, off
	global_store_short v[250:251], v239, off
	v_mov_b32_e32 v76, v193
	v_add_u32_e32 v83, v161, v155
	v_add_u32_e32 v82, v181, v182
	v_add_u32_e32 v84, v161, v182
	v_add_u32_e32 v85, v161, v183
	v_add_u32_e32 v86, v161, v162
	ds_read_b128 v[88:91], v83 offset:34816
	ds_read_b128 v[92:95], v82 offset:34816
	ds_read_b128 v[96:99], v190 offset:34816
	ds_read_b128 v[100:103], v191 offset:34816
	ds_read_b128 v[104:107], v83 offset:44096
	ds_read_b128 v[194:197], v84 offset:46400
	ds_read_b128 v[198:201], v85 offset:48704
	ds_read_b128 v[232:235], v86 offset:51008
	s_waitcnt lgkmcnt(8)
; #define LAS __attribute__((address_space(3)))
; __device__ __forceinline__ bf16_t f2bf(float f) { return (bf16_t)(pk2(f, f) & 0xFFFFu); }
; #define MFMA16(a, b, c) __builtin_amdgcn_mfma_f32_16x16x32_bf16((a), (b), (c), 0, 0, 0)
; template <int MODE>
; __device__ NOINL void chain_item(const LAS Params* lp, int l, int item, bool ctx_out, LAS unsigned char* lds) {
;     ...
;     for (int n = 0; n < 36; ++n) {
;         const int cid = n < 4 ? (dir ? 3 - n : n) : (dir ? 39 - n : n);
;         int row0, t0, L; chunk_geom(b, cid, row0, t0, L);
;         __syncthreads();
;         u32x4 kk0 = rk[0], kk1 = rk[1];
;         *(LAS u32x4*)(Qs + pp * 136 + lrow) = rq[0]; *(LAS u32x4*)(Qs + pp * 136 + lrow + 8) = rq[1];
;         *(LAS u32x4*)(Ks + pp * 136 + lrow) = kk0; *(LAS u32x4*)(Ks + pp * 136 + lrow + 8) = kk1;
;         {
;             const unsigned vv[8] = {rv[0].x, rv[0].y, rv[0].z, rv[0].w, rv[1].x, rv[1].y, rv[1].z, rv[1].w};
; #pragma unroll
;             for (int e = 0; e < 8; ++e) { VT[(lrow + 2 * e) * 72 + ppz] = (bf16_t)(vv[e] & 0xFFFFu); VT[(lrow + 2 * e + 1) * 72 + ppz] = (bf16_t)(vv[e] >> 16); }
;         }
;         if (MODE == 0) {
;             *(LAS u32x4*)(TT + (tid >> 3) * 72 + (tid & 7) * 8) = rt;
;             if (tid < 192) gcs[tid] = rg;
;         } else {
;             const float ksc = __expf((float)(63 - pp) * lgl);
;             float kf[16]; unpack8(kk0, kf); unpack8(kk1, kf + 8);
; #pragma unroll
;             for (int e = 0; e < 16; ++e) KT[(lrow + e) * 72 + ppz] = f2bf(kf[e] * ksc);
;         }
;         __syncthreads();
;         if (n + 1 < 36) issue(n + 1);
;     ...
;             const float gl = MODE == 0 ? gcs[128 + 63] : __expf(64.f * lg);
; #pragma unroll
;             for (int dk = 0; dk < NDK; ++dk) {
;                 Sacc[dk] = Sacc[dk] * gl;
; #pragma unroll
;                 for (int ks = 0; ks < 2; ++ks) { const bf16x8 A = *(const LAS bf16x8*)(KT + (kcol + 16 * dk + fr) * 72 + (((ks * 4 + fq) ^ (((kcol >> 4) + dk) & 7)) << 3)); Sacc[dk] = MFMA16(A, Bv[ks], Sacc[dk]); }
	v_pk_mul_f32 v[30:31], v[30:31], v[76:77] op_sel_hi:[1,0]
	v_pk_mul_f32 v[28:29], v[28:29], v[76:77] op_sel_hi:[1,0]
	v_pk_mul_f32 v[42:43], v[42:43], v[76:77] op_sel_hi:[1,0]
	v_pk_mul_f32 v[40:41], v[40:41], v[76:77] op_sel_hi:[1,0]
	v_pk_mul_f32 v[34:35], v[34:35], v[76:77] op_sel_hi:[1,0]
	v_pk_mul_f32 v[32:33], v[32:33], v[76:77] op_sel_hi:[1,0]
	v_pk_mul_f32 v[38:39], v[38:39], v[76:77] op_sel_hi:[1,0]
	v_pk_mul_f32 v[36:37], v[36:37], v[76:77] op_sel_hi:[1,0]
	v_pk_mul_f32 v[58:59], v[58:59], v[76:77] op_sel_hi:[1,0]
	v_pk_mul_f32 v[56:57], v[56:57], v[76:77] op_sel_hi:[1,0]
	v_pk_mul_f32 v[54:55], v[54:55], v[76:77] op_sel_hi:[1,0]
	v_pk_mul_f32 v[52:53], v[52:53], v[76:77] op_sel_hi:[1,0]
	v_pk_mul_f32 v[46:47], v[46:47], v[76:77] op_sel_hi:[1,0]
	v_pk_mul_f32 v[44:45], v[44:45], v[76:77] op_sel_hi:[1,0]
	v_pk_mul_f32 v[50:51], v[50:51], v[76:77] op_sel_hi:[1,0]
	v_pk_mul_f32 v[48:49], v[48:49], v[76:77] op_sel_hi:[1,0]
	s_waitcnt lgkmcnt(7)
	v_mfma_f32_16x16x32_bf16 v[28:31], v[88:91], v[72:75], v[28:31]
	ds_read_b128 v[88:91], v83 offset:34880
	s_waitcnt lgkmcnt(7)
	v_mfma_f32_16x16x32_bf16 v[40:43], v[92:95], v[72:75], v[40:43]
	ds_read_b128 v[92:95], v82 offset:34880
	s_waitcnt lgkmcnt(7)
	v_mfma_f32_16x16x32_bf16 v[32:35], v[96:99], v[72:75], v[32:35]
	ds_read_b128 v[96:99], v190 offset:34880
	s_waitcnt lgkmcnt(7)
	v_mfma_f32_16x16x32_bf16 v[36:39], v[100:103], v[72:75], v[36:39]
	ds_read_b128 v[100:103], v191 offset:34880
	s_waitcnt lgkmcnt(7)
	v_mfma_f32_16x16x32_bf16 v[56:59], v[104:107], v[72:75], v[56:59]
	ds_read_b128 v[104:107], v83 offset:44032
	s_waitcnt lgkmcnt(7)
	v_mfma_f32_16x16x32_bf16 v[52:55], v[194:197], v[72:75], v[52:55]
	ds_read_b128 v[194:197], v84 offset:46336
	s_waitcnt lgkmcnt(7)
	v_mfma_f32_16x16x32_bf16 v[44:47], v[198:201], v[72:75], v[44:47]
	ds_read_b128 v[198:201], v85 offset:48640
	s_waitcnt lgkmcnt(7)
	v_mfma_f32_16x16x32_bf16 v[48:51], v[232:235], v[72:75], v[48:51]
	ds_read_b128 v[232:235], v86 offset:50944
	s_waitcnt lgkmcnt(7)
	v_mfma_f32_16x16x32_bf16 v[28:31], v[88:91], v[68:71], v[28:31]
	s_waitcnt lgkmcnt(6)
	v_mfma_f32_16x16x32_bf16 v[40:43], v[92:95], v[68:71], v[40:43]
	s_waitcnt lgkmcnt(5)
	v_mfma_f32_16x16x32_bf16 v[32:35], v[96:99], v[68:71], v[32:35]
	s_waitcnt lgkmcnt(4)
	v_mfma_f32_16x16x32_bf16 v[36:39], v[100:103], v[68:71], v[36:39]
	s_waitcnt lgkmcnt(3)
	v_mfma_f32_16x16x32_bf16 v[56:59], v[104:107], v[68:71], v[56:59]
	s_waitcnt lgkmcnt(2)
	v_mfma_f32_16x16x32_bf16 v[52:55], v[194:197], v[68:71], v[52:55]
	s_waitcnt lgkmcnt(1)
	v_mfma_f32_16x16x32_bf16 v[44:47], v[198:201], v[68:71], v[44:47]
	s_waitcnt lgkmcnt(0)
	v_mfma_f32_16x16x32_bf16 v[48:51], v[232:235], v[68:71], v[48:51]
	s_waitcnt vmcnt(19)
	v_mov_b64_e32 v[74:75], v[66:67]
	v_mov_b64_e32 v[70:71], v[62:63]
	v_mov_b64_e32 v[72:73], v[64:65]
	v_mov_b64_e32 v[68:69], v[60:61]
	s_cbranch_scc0 .LBB0_1135
.LBB0_1142:
	s_waitcnt vmcnt(5)
	ds_write_b128 v151, v[12:15]
	ds_write_b128 v151, v[8:11] offset:16
	s_waitcnt vmcnt(3)
	ds_write_b128 v151, v[72:75] offset:17408
	ds_write_b128 v151, v[68:71] offset:17424
	s_waitcnt vmcnt(1)
	ds_write_b16 v163, v20 offset:53248
	ds_write_b16_d16_hi v163, v20 offset:53392
	ds_write_b16 v163, v21 offset:53536
	ds_write_b16_d16_hi v163, v21 offset:53680
	ds_write_b16 v163, v22 offset:53824
	ds_write_b16_d16_hi v163, v22 offset:53968
	ds_write_b16 v163, v23 offset:54112
	ds_write_b16_d16_hi v163, v23 offset:54256
	ds_write_b16 v163, v16 offset:54400
	ds_write_b16_d16_hi v163, v16 offset:54544
	ds_write_b16 v163, v17 offset:54688
	ds_write_b16_d16_hi v163, v17 offset:54832
	ds_write_b16 v163, v18 offset:54976
	ds_write_b16_d16_hi v163, v18 offset:55120
	ds_write_b16 v163, v19 offset:55264
	ds_write_b16_d16_hi v163, v19 offset:55408
	s_waitcnt vmcnt(0)
	ds_write_b128 v152, v[24:27]
	s_and_saveexec_b64 s[62:63], s[44:45]
	ds_write_b32 v156, v150
	s_or_b64 exec, exec, s[62:63]
	s_add_i32 s0, s1, 1
	s_cmp_eq_u32 s1, 35
	s_waitcnt lgkmcnt(0)
	s_barrier
	s_cbranch_scc1 .LBB0_1148
	s_cmp_lt_u32 s1, 3
	s_cselect_b32 s5, 3, 39
	s_add_i32 s5, s5, s4
	s_and_b64 s[20:21], vcc, exec
	s_cselect_b32 s5, s0, s5
	s_cmp_lt_i32 s5, 4
	s_cselect_b32 s20, 8, 11
	s_cselect_b32 s21, 0x8000, s14
	s_lshl_b32 s20, s29, s20
	s_lshl_b32 s22, s5, 6
	s_add_i32 s20, s20, s21
	s_add_i32 s20, s20, s22
	v_add_u32_e32 v8, s20, v111
	v_mad_i64_i32 v[20:21], s[20:21], v8, s81, v[2:3]
	s_ashr_i32 s20, s5, 31
	global_load_dwordx4 v[8:11], v[20:21], off offset:16
	global_load_dwordx4 v[12:15], v[20:21], off
	global_load_dwordx4 v[60:63], v[20:21], off offset:1040
	global_load_dwordx4 v[64:67], v[20:21], off offset:1024
	global_load_dwordx4 v[16:19], v[20:21], off offset:2064
	s_nop 0
	global_load_dwordx4 v[20:23], v[20:21], off offset:2048
	s_add_u32 s64, s39, s5
	s_addc_u32 s65, s41, s20
	s_lshl_b64 s[20:21], s[64:65], 14
	v_lshl_add_u64 v[24:25], v[108:109], 0, s[20:21]
	global_load_dwordx4 v[24:27], v[24:25], off
	s_and_saveexec_b64 s[62:63], s[44:45]
	s_cbranch_execz .LBB0_1147
	s_lshl_b64 s[20:21], s[64:65], 1
	s_or_b32 s5, s20, s27
	s_mul_i32 s22, s21, 0x300
	v_mad_u64_u32 v[76:77], s[20:21], s5, v229, v[114:115]
	v_add_u32_e32 v77, s22, v77
	global_load_dword v150, v[76:77], off
